# epilogue de-serialisation: the group-0 window-attention combine fetches the lse / o rows of all four row groups together instead of one load round trip per row group behind the previous store
# baseline (speedup 1.0000x reference)
; __device__ __forceinline__ int crow(int r, int hi) { return (r & 3) + 8 * (r >> 2) + 4 * hi; }
; __device__ __forceinline__ unsigned cvtpk(float lo, float hi) { return pg8::cvt_pk_bf16(lo, hi); }
; __device__ __forceinline__ void sub_unit(int dil, int Lsub, int nres, int r0, int t0, const bf16* qp, const bf16* __restrict__ kp, const bf16* __restrict__ vp, bf16* op, float* lse, char* lds, const bf16* c1 = nullptr, const bf16* c2 = nullptr, const float* l1 = nullptr, const float* l2 = nullptr) {
;     ...
;   float* ws = (float*)(lds + WS_OFF) + wid * 64;
;   if (hi == 0) { ws[r32] = den; const float ls = mx + __builtin_amdgcn_logf(den); if (c1) ws[32 + r32] = ls; else lse[((long)(tq0 + r32) * dil + r) * 8] = ls; }
;   asm volatile("s_waitcnt lgkmcnt(0)" ::: "memory");
;   { bf16* stg = (bf16*)(lds + ST_OFF) + wid * 2048;
; #pragma unroll
;     for (int r_ = 0; r_ < 16; ++r_) { const int orow = crow(r_, hi); const float rl = __builtin_amdgcn_rcpf(ws[orow]);
; #pragma unroll
;       for (int d0 = 0; d0 < 2; ++d0) stg[orow * 64 + d0 * 32 + r32] = (bf16)(cvtpk(o[d0][r_] * rl, 0.f) & 0xffffu); }
;     asm volatile("s_waitcnt lgkmcnt(0)" ::: "memory");
; #pragma unroll
;     for (int i = 0; i < 4; ++i) { const int row = i * 8 + (lane >> 3), ch = lane & 7; u32x4 v = *(const u32x4*)(stg + row * 64 + ch * 8);
;       const long off = ((long)(tq0 + row) * dil + r) * LD + ch * 8;
;       if (c1) { const long tok = (long)(tq0 + row); const float a0 = ws[32 + row], a1 = __builtin_nontemporal_load(l1 + tok * 8), a2 = __builtin_nontemporal_load(l2 + tok * 8); const u32x4 x1 = __builtin_nontemporal_load((const u32x4*)(c1 + off)), x2 = __builtin_nontemporal_load((const u32x4*)(c2 + off));
.LBB0_342:
	s_or_b64 exec, exec, s[22:23]
	s_add_u32 s22, s48, s60
	s_waitcnt lgkmcnt(0)
	v_lshl_add_u32 v40, v96, 2, s11
	s_addc_u32 s23, s49, 0
	ds_read_b128 v[32:35], v40
	ds_read_b128 v[36:39], v40 offset:32
	s_add_u32 s38, s50, s60
	s_addc_u32 s39, s51, 0
	s_lshl_b32 s12, s58, 2
	s_lshl_b32 s13, s59, 5
	s_or_b32 s12, s13, s12
	s_add_u32 s40, s52, s12
	s_addc_u32 s41, s53, 0
	s_waitcnt lgkmcnt(1)
	v_rcp_f32_e32 v32, v32
	s_add_u32 s42, s54, s12
	s_addc_u32 s43, s55, 0
	s_add_i32 s10, s10, 0
	s_add_i32 s10, s10, 0x18000
	v_lshl_add_u32 v41, v98, 1, s10
	v_mul_f32_e32 v16, v16, v32
	v_lshl_add_u32 v42, v99, 9, v41
	v_cvt_pk_bf16_f32 v16, v16, s0
	ds_write_b16 v42, v16
	v_rcp_f32_e32 v16, v33
	v_mul_f32_e32 v0, v0, v32
	v_cvt_pk_bf16_f32 v0, v0, s0
	ds_write_b16 v42, v0 offset:64
	v_mul_f32_e32 v17, v17, v16
	v_mul_f32_e32 v1, v1, v16
	v_rcp_f32_e32 v16, v34
	v_lshl_add_u32 v0, v95, 7, v41
	v_cvt_pk_bf16_f32 v1, v1, s0
	v_cvt_pk_bf16_f32 v17, v17, s0
	ds_write_b16 v0, v1 offset:64
	v_mul_f32_e32 v1, v18, v16
	ds_write_b16 v0, v17
	v_lshl_add_u32 v0, v94, 7, v41
	v_cvt_pk_bf16_f32 v1, v1, s0
	ds_write_b16 v0, v1
	v_mul_f32_e32 v1, v2, v16
	v_rcp_f32_e32 v2, v35
	v_cvt_pk_bf16_f32 v1, v1, s0
	ds_write_b16 v0, v1 offset:64
	v_lshl_add_u32 v0, v93, 7, v41
	v_mul_f32_e32 v1, v19, v2
	v_cvt_pk_bf16_f32 v1, v1, s0
	ds_write_b16 v0, v1
	v_mul_f32_e32 v1, v3, v2
	s_waitcnt lgkmcnt(7)
	v_rcp_f32_e32 v2, v36
	v_cvt_pk_bf16_f32 v1, v1, s0
	ds_write_b16 v0, v1 offset:64
	v_lshl_add_u32 v0, v92, 7, v41
	v_mul_f32_e32 v1, v20, v2
	v_cvt_pk_bf16_f32 v1, v1, s0
	ds_write_b16 v0, v1
	v_mul_f32_e32 v1, v4, v2
	v_rcp_f32_e32 v2, v37
	v_cvt_pk_bf16_f32 v1, v1, s0
	ds_write_b16 v0, v1 offset:64
	v_lshl_add_u32 v0, v91, 7, v41
	v_mul_f32_e32 v1, v21, v2
	v_cvt_pk_bf16_f32 v1, v1, s0
	ds_write_b16 v0, v1
	v_mul_f32_e32 v1, v5, v2
	v_rcp_f32_e32 v2, v38
	v_cvt_pk_bf16_f32 v1, v1, s0
	ds_write_b16 v0, v1 offset:64
	v_lshl_add_u32 v0, v90, 7, v41
	v_mul_f32_e32 v1, v22, v2
	v_cvt_pk_bf16_f32 v1, v1, s0
	ds_write_b16 v0, v1
	v_mul_f32_e32 v1, v6, v2
	v_rcp_f32_e32 v4, v39
	v_cvt_pk_bf16_f32 v1, v1, s0
	ds_write_b16 v0, v1 offset:64
	ds_read_b128 v[0:3], v40 offset:64
	v_mul_f32_e32 v5, v23, v4
	v_lshl_add_u32 v16, v89, 7, v41
	v_cvt_pk_bf16_f32 v5, v5, s0
	ds_write_b16 v16, v5
	v_mul_f32_e32 v17, v7, v4
	ds_read_b128 v[4:7], v40 offset:96
	s_waitcnt lgkmcnt(2)
	v_rcp_f32_e32 v0, v0
	v_rcp_f32_e32 v1, v1
	v_cvt_pk_bf16_f32 v17, v17, s0
	v_rcp_f32_e32 v2, v2
	ds_write_b16 v16, v17 offset:64
	v_mul_f32_e32 v17, v24, v0
	v_mul_f32_e32 v0, v8, v0
	v_lshl_add_u32 v16, v88, 7, v41
	v_cvt_pk_bf16_f32 v0, v0, s0
	v_mul_f32_e32 v8, v25, v1
	v_mul_f32_e32 v1, v9, v1
	ds_write_b16 v16, v0 offset:64
	v_lshl_add_u32 v0, v87, 7, v41
	v_cvt_pk_bf16_f32 v1, v1, s0
	v_cvt_pk_bf16_f32 v8, v8, s0
	ds_write_b16 v0, v1 offset:64
	v_mul_f32_e32 v1, v26, v2
	ds_write_b16 v0, v8
	v_lshl_add_u32 v0, v86, 7, v41
	v_cvt_pk_bf16_f32 v1, v1, s0
	ds_write_b16 v0, v1
	v_mul_f32_e32 v1, v10, v2
	v_rcp_f32_e32 v2, v3
	v_cvt_pk_bf16_f32 v1, v1, s0
	ds_write_b16 v0, v1 offset:64
	v_lshl_add_u32 v0, v85, 7, v41
	v_mul_f32_e32 v1, v27, v2
	v_cvt_pk_bf16_f32 v1, v1, s0
	ds_write_b16 v0, v1
	v_mul_f32_e32 v1, v11, v2
	s_waitcnt lgkmcnt(7)
	v_rcp_f32_e32 v2, v4
	v_cvt_pk_bf16_f32 v1, v1, s0
	ds_write_b16 v0, v1 offset:64
	v_lshl_add_u32 v0, v83, 7, v41
	v_mul_f32_e32 v1, v28, v2
	v_cvt_pk_bf16_f32 v1, v1, s0
	ds_write_b16 v0, v1
	v_mul_f32_e32 v1, v12, v2
	v_rcp_f32_e32 v2, v5
	v_cvt_pk_bf16_f32 v1, v1, s0
	ds_write_b16 v0, v1 offset:64
	v_lshl_add_u32 v0, v82, 7, v41
	v_mul_f32_e32 v1, v29, v2
	v_cvt_pk_bf16_f32 v1, v1, s0
	ds_write_b16 v0, v1
	v_mul_f32_e32 v1, v13, v2
	v_rcp_f32_e32 v2, v6
	v_cvt_pk_bf16_f32 v1, v1, s0
	ds_write_b16 v0, v1 offset:64
	v_lshl_add_u32 v0, v81, 7, v41
	v_mul_f32_e32 v1, v30, v2
	v_cvt_pk_bf16_f32 v1, v1, s0
	ds_write_b16 v0, v1
	v_mul_f32_e32 v1, v14, v2
	v_rcp_f32_e32 v2, v7
	v_cvt_pk_bf16_f32 v1, v1, s0
	ds_write_b16 v0, v1 offset:64
	v_lshl_add_u32 v0, v80, 7, v41
	v_mul_f32_e32 v1, v31, v2
	v_cvt_pk_bf16_f32 v1, v1, s0
	ds_write_b16 v0, v1
	v_mul_f32_e32 v1, v15, v2
	v_cvt_pk_bf16_f32 v1, v1, s0
	v_lshrrev_b32_e32 v19, 3, v84
	ds_write_b16 v0, v1 offset:64
	v_or_b32_e32 v0, s57, v19
	v_cvt_pk_bf16_f32 v17, v17, s0
	v_ashrrev_i32_e32 v1, 31, v0
	ds_write_b16 v16, v17
	v_lshlrev_b64 v[2:3], 5, v[0:1]
	s_waitcnt lgkmcnt(0)
	v_lshl_add_u64 v[4:5], s[40:41], 0, v[2:3]
	v_lshl_add_u64 v[2:3], s[42:43], 0, v[2:3]
	global_load_dword v8, v[4:5], off nt
	global_load_dword v9, v[2:3], off nt
	v_lshlrev_b64 v[12:13], 10, v[0:1]
	v_or_b32_e32 v12, v12, v188
	v_lshl_add_u64 v[0:1], s[22:23], 0, v[12:13]
	global_load_dwordx4 v[0:3], v[0:1], off nt
	v_lshl_add_u64 v[4:5], s[38:39], 0, v[12:13]
	global_load_dwordx4 v[4:7], v[4:5], off nt
	v_or_b32_e32 v146, 8, v19
	v_or_b32_e32 v146, s57, v146
	v_ashrrev_i32_e32 v147, 31, v146
	v_lshlrev_b64 v[148:149], 5, v[146:147]
	v_lshl_add_u64 v[150:151], s[40:41], 0, v[148:149]
	global_load_dword v154, v[150:151], off nt
	v_lshl_add_u64 v[150:151], s[42:43], 0, v[148:149]
	global_load_dword v155, v[150:151], off nt
	v_lshlrev_b64 v[148:149], 10, v[146:147]
	v_or_b32_e32 v148, v148, v188
	v_lshl_add_u64 v[150:151], s[22:23], 0, v[148:149]
	global_load_dwordx4 v[156:159], v[150:151], off nt
	v_lshl_add_u64 v[150:151], s[38:39], 0, v[148:149]
	global_load_dwordx4 v[160:163], v[150:151], off nt
	v_or_b32_e32 v146, 16, v19
	v_or_b32_e32 v146, s57, v146
	v_ashrrev_i32_e32 v147, 31, v146
	v_lshlrev_b64 v[148:149], 5, v[146:147]
	v_lshl_add_u64 v[150:151], s[40:41], 0, v[148:149]
	global_load_dword v164, v[150:151], off nt
	v_lshl_add_u64 v[150:151], s[42:43], 0, v[148:149]
	global_load_dword v165, v[150:151], off nt
	v_lshlrev_b64 v[148:149], 10, v[146:147]
	v_or_b32_e32 v148, v148, v188
	v_lshl_add_u64 v[150:151], s[22:23], 0, v[148:149]
	global_load_dwordx4 v[166:169], v[150:151], off nt
	v_lshl_add_u64 v[150:151], s[38:39], 0, v[148:149]
	global_load_dwordx4 v[170:173], v[150:151], off nt
	v_or_b32_e32 v146, 24, v19
	v_or_b32_e32 v146, s57, v146
	v_ashrrev_i32_e32 v147, 31, v146
	v_lshlrev_b64 v[148:149], 5, v[146:147]
	v_lshl_add_u64 v[150:151], s[40:41], 0, v[148:149]
	global_load_dword v174, v[150:151], off nt
	v_lshl_add_u64 v[150:151], s[42:43], 0, v[148:149]
	global_load_dword v175, v[150:151], off nt
	v_lshlrev_b64 v[148:149], 10, v[146:147]
	v_or_b32_e32 v148, v148, v188
	v_lshl_add_u64 v[150:151], s[22:23], 0, v[148:149]
	global_load_dwordx4 v[176:179], v[150:151], off nt
	v_lshl_add_u64 v[150:151], s[38:39], 0, v[148:149]
	global_load_dwordx4 v[180:183], v[150:151], off nt
	v_lshl_add_u32 v26, v19, 2, s11
	ds_read2_b32 v[14:15], v26 offset0:32 offset1:40
	v_add_u32_e32 v27, s10, v188
	v_readlane_b32 s10, v255, 14
	s_add_i32 s8, s8, s10
	v_readlane_b32 s10, v255, 16
	s_add_i32 s56, s56, s46
	s_add_i32 s3, s3, s10
	s_cmpk_gt_i32 s56, 0x3ff
	s_waitcnt vmcnt(14) lgkmcnt(0)
; __device__ __forceinline__ unsigned cvtpk(float lo, float hi) { return pg8::cvt_pk_bf16(lo, hi); }
; __device__ __forceinline__ float blo(unsigned w) { return __uint_as_float(w << 16); }
; __device__ __forceinline__ float bhi(unsigned w) { return __uint_as_float(w & 0xffff0000u); }
; __device__ __forceinline__ void sub_unit(int dil, int Lsub, int nres, int r0, int t0, const bf16* qp, const bf16* __restrict__ kp, const bf16* __restrict__ vp, bf16* op, float* lse, char* lds, const bf16* c1 = nullptr, const bf16* c2 = nullptr, const float* l1 = nullptr, const float* l2 = nullptr) {
;     ...
;     for (int i = 0; i < 4; ++i) { const int row = i * 8 + (lane >> 3), ch = lane & 7; u32x4 v = *(const u32x4*)(stg + row * 64 + ch * 8);
;       const long off = ((long)(tq0 + row) * dil + r) * LD + ch * 8;
;       if (c1) { const long tok = (long)(tq0 + row); const float a0 = ws[32 + row], a1 = __builtin_nontemporal_load(l1 + tok * 8), a2 = __builtin_nontemporal_load(l2 + tok * 8); const u32x4 x1 = __builtin_nontemporal_load((const u32x4*)(c1 + off)), x2 = __builtin_nontemporal_load((const u32x4*)(c2 + off));
;         const float mxl = fmaxf(a0, fmaxf(a1, a2)); float w0 = __builtin_amdgcn_exp2f(a0 - mxl), w1 = __builtin_amdgcn_exp2f(a1 - mxl), w2 = __builtin_amdgcn_exp2f(a2 - mxl); const float inv = __builtin_amdgcn_rcpf(w0 + w1 + w2); w0 *= inv; w1 *= inv; w2 *= inv;
; #pragma unroll
;         for (int k = 0; k < 4; ++k) { const float lo = w0 * blo(v[k]) + w1 * blo(x1[k]) + w2 * blo(x2[k]), hh = w0 * bhi(v[k]) + w1 * bhi(x1[k]) + w2 * bhi(x2[k]); v[k] = cvtpk(lo, hh); } }
;       *(u32x4*)(op + off) = v; } }
	v_max3_f32 v10, v14, v8, v9
	v_sub_f32_e32 v11, v14, v10
	v_sub_f32_e32 v8, v8, v10
	v_exp_f32_e32 v17, v11
	v_exp_f32_e32 v16, v8
	v_sub_f32_e32 v8, v9, v10
	v_exp_f32_e32 v18, v8
	s_waitcnt vmcnt(13)
	v_and_b32_e32 v23, 0xffff0000, v0
	v_add_f32_e32 v8, v17, v16
	v_lshlrev_b32_e32 v20, 16, v0
	v_add_f32_e32 v8, v18, v8
	v_rcp_f32_e32 v14, v8
	v_lshl_add_u32 v8, v19, 7, v27
	ds_read_b128 v[8:11], v8
	s_waitcnt vmcnt(12)
	v_lshlrev_b32_e32 v24, 16, v4
	v_pk_mul_f32 v[16:17], v[16:17], v[14:15] op_sel_hi:[1,0]
	v_mul_f32_e32 v18, v18, v14
	v_and_b32_e32 v25, 0xffff0000, v4
	s_waitcnt lgkmcnt(0)
	v_lshlrev_b32_e32 v22, 16, v8
	v_and_b32_e32 v21, 0xffff0000, v8
	v_pk_mul_f32 v[22:23], v[16:17], v[22:23] op_sel:[1,0] op_sel_hi:[0,1]
	v_pk_fma_f32 v[20:21], v[16:17], v[20:21], v[22:23]
	v_lshlrev_b32_e32 v8, 16, v9
	v_pk_fma_f32 v[20:21], v[18:19], v[24:25], v[20:21] op_sel_hi:[0,1,1]
	v_cvt_pk_bf16_f32 v0, v20, v21
	v_and_b32_e32 v21, 0xffff0000, v9
	v_and_b32_e32 v9, 0xffff0000, v1
	v_lshlrev_b32_e32 v20, 16, v1
	v_pk_mul_f32 v[8:9], v[16:17], v[8:9] op_sel:[1,0] op_sel_hi:[0,1]
	v_lshlrev_b32_e32 v4, 16, v5
	v_and_b32_e32 v5, 0xffff0000, v5
	v_pk_fma_f32 v[8:9], v[16:17], v[20:21], v[8:9]
	v_lshlrev_b32_e32 v20, 16, v6
	v_pk_fma_f32 v[4:5], v[18:19], v[4:5], v[8:9] op_sel_hi:[0,1,1]
	v_lshlrev_b32_e32 v8, 16, v10
	v_and_b32_e32 v9, 0xffff0000, v2
	v_cvt_pk_bf16_f32 v1, v4, v5
	v_lshlrev_b32_e32 v4, 16, v2
	v_and_b32_e32 v5, 0xffff0000, v10
	v_pk_mul_f32 v[8:9], v[16:17], v[8:9] op_sel:[1,0] op_sel_hi:[0,1]
	v_and_b32_e32 v21, 0xffff0000, v6
	v_pk_fma_f32 v[4:5], v[16:17], v[4:5], v[8:9]
	v_lshlrev_b32_e32 v8, 16, v11
	v_pk_fma_f32 v[4:5], v[18:19], v[20:21], v[4:5] op_sel_hi:[0,1,1]
	v_and_b32_e32 v9, 0xffff0000, v3
	v_cvt_pk_bf16_f32 v2, v4, v5
	v_lshlrev_b32_e32 v4, 16, v3
	v_and_b32_e32 v5, 0xffff0000, v11
	v_pk_mul_f32 v[8:9], v[16:17], v[8:9] op_sel:[1,0] op_sel_hi:[0,1]
	v_pk_fma_f32 v[4:5], v[16:17], v[4:5], v[8:9]
	v_lshlrev_b32_e32 v6, 16, v7
	v_and_b32_e32 v7, 0xffff0000, v7
	v_pk_fma_f32 v[4:5], v[18:19], v[6:7], v[4:5] op_sel_hi:[0,1,1]
	v_cvt_pk_bf16_f32 v3, v4, v5
	v_lshl_add_u64 v[4:5], s[16:17], 0, v[12:13]
	v_or_b32_e32 v8, 8, v19
	global_store_dwordx4 v[4:5], v[0:3], off
	s_nop 1
	v_or_b32_e32 v0, s57, v8
	v_ashrrev_i32_e32 v1, 31, v0
	v_lshlrev_b64 v[2:3], 5, v[0:1]
	v_lshl_add_u64 v[4:5], s[40:41], 0, v[2:3]
	v_lshl_add_u64 v[2:3], s[42:43], 0, v[2:3]
	v_lshlrev_b64 v[12:13], 10, v[0:1]
	v_or_b32_e32 v12, v12, v188
	v_lshl_add_u64 v[0:1], s[22:23], 0, v[12:13]
	v_lshl_add_u64 v[4:5], s[38:39], 0, v[12:13]
	v_lshl_add_u32 v8, v8, 7, v27
	s_waitcnt vmcnt(11)
	v_mov_b32_e32 v9, v154
	v_mov_b32_e32 v10, v155
	v_max3_f32 v11, v15, v9, v10
	v_sub_f32_e32 v14, v15, v11
	v_sub_f32_e32 v9, v9, v11
	v_exp_f32_e32 v15, v14
	v_exp_f32_e32 v14, v9
	v_sub_f32_e32 v9, v10, v11
	v_exp_f32_e32 v17, v9
	s_waitcnt vmcnt(10)
	v_mov_b64_e32 v[0:1], v[156:157]
	v_mov_b64_e32 v[2:3], v[158:159]
	v_and_b32_e32 v21, 0xffff0000, v0
	v_add_f32_e32 v9, v15, v14
	s_waitcnt vmcnt(9)
	v_mov_b64_e32 v[4:5], v[160:161]
	v_mov_b64_e32 v[6:7], v[162:163]
	v_lshlrev_b32_e32 v22, 16, v4
	v_add_f32_e32 v9, v17, v9
	v_rcp_f32_e32 v16, v9
	ds_read_b128 v[8:11], v8
	v_and_b32_e32 v23, 0xffff0000, v4
	v_lshlrev_b32_e32 v4, 16, v5
	v_pk_mul_f32 v[14:15], v[14:15], v[16:17] op_sel_hi:[1,0]
	v_mul_f32_e32 v18, v17, v16
	s_waitcnt lgkmcnt(0)
	v_lshlrev_b32_e32 v20, 16, v8
	v_lshlrev_b32_e32 v16, 16, v0
	v_and_b32_e32 v17, 0xffff0000, v8
	v_pk_mul_f32 v[20:21], v[14:15], v[20:21] op_sel:[1,0] op_sel_hi:[0,1]
	v_pk_fma_f32 v[16:17], v[14:15], v[16:17], v[20:21]
	v_lshlrev_b32_e32 v8, 16, v9
	v_pk_fma_f32 v[16:17], v[18:19], v[22:23], v[16:17] op_sel_hi:[0,1,1]
	v_cvt_pk_bf16_f32 v0, v16, v17
	v_and_b32_e32 v17, 0xffff0000, v9
	v_and_b32_e32 v9, 0xffff0000, v1
	v_lshlrev_b32_e32 v16, 16, v1
	v_pk_mul_f32 v[8:9], v[14:15], v[8:9] op_sel:[1,0] op_sel_hi:[0,1]
	v_and_b32_e32 v5, 0xffff0000, v5
	v_pk_fma_f32 v[8:9], v[14:15], v[16:17], v[8:9]
	v_lshlrev_b32_e32 v16, 16, v6
	v_pk_fma_f32 v[4:5], v[18:19], v[4:5], v[8:9] op_sel_hi:[0,1,1]
	v_lshlrev_b32_e32 v8, 16, v10
	v_and_b32_e32 v9, 0xffff0000, v2
	v_cvt_pk_bf16_f32 v1, v4, v5
	v_lshlrev_b32_e32 v4, 16, v2
	v_and_b32_e32 v5, 0xffff0000, v10
	v_pk_mul_f32 v[8:9], v[14:15], v[8:9] op_sel:[1,0] op_sel_hi:[0,1]
	v_and_b32_e32 v17, 0xffff0000, v6
	v_pk_fma_f32 v[4:5], v[14:15], v[4:5], v[8:9]
	v_lshlrev_b32_e32 v8, 16, v11
	v_pk_fma_f32 v[4:5], v[18:19], v[16:17], v[4:5] op_sel_hi:[0,1,1]
	v_and_b32_e32 v9, 0xffff0000, v3
	v_cvt_pk_bf16_f32 v2, v4, v5
	v_lshlrev_b32_e32 v4, 16, v3
	v_and_b32_e32 v5, 0xffff0000, v11
	v_pk_mul_f32 v[8:9], v[14:15], v[8:9] op_sel:[1,0] op_sel_hi:[0,1]
	v_pk_fma_f32 v[4:5], v[14:15], v[4:5], v[8:9]
	v_lshlrev_b32_e32 v6, 16, v7
	v_and_b32_e32 v7, 0xffff0000, v7
	v_pk_fma_f32 v[4:5], v[18:19], v[6:7], v[4:5] op_sel_hi:[0,1,1]
	v_cvt_pk_bf16_f32 v3, v4, v5
	v_lshl_add_u64 v[4:5], s[16:17], 0, v[12:13]
	v_or_b32_e32 v8, 16, v19
	global_store_dwordx4 v[4:5], v[0:3], off
	s_nop 1
	v_or_b32_e32 v0, s57, v8
	v_ashrrev_i32_e32 v1, 31, v0
	v_lshlrev_b64 v[2:3], 5, v[0:1]
	v_lshl_add_u64 v[4:5], s[40:41], 0, v[2:3]
	v_lshl_add_u64 v[2:3], s[42:43], 0, v[2:3]
	v_lshlrev_b64 v[12:13], 10, v[0:1]
	v_or_b32_e32 v12, v12, v188
	v_lshl_add_u64 v[0:1], s[22:23], 0, v[12:13]
	v_lshl_add_u64 v[4:5], s[38:39], 0, v[12:13]
	ds_read2_b32 v[14:15], v26 offset0:48 offset1:56
	v_lshl_add_u32 v8, v8, 7, v27
	s_waitcnt vmcnt(8) lgkmcnt(0)
; __device__ __forceinline__ unsigned cvtpk(float lo, float hi) { return pg8::cvt_pk_bf16(lo, hi); }
; __device__ __forceinline__ float blo(unsigned w) { return __uint_as_float(w << 16); }
; __device__ __forceinline__ float bhi(unsigned w) { return __uint_as_float(w & 0xffff0000u); }
; __device__ __forceinline__ void sub_unit(int dil, int Lsub, int nres, int r0, int t0, const bf16* qp, const bf16* __restrict__ kp, const bf16* __restrict__ vp, bf16* op, float* lse, char* lds, const bf16* c1 = nullptr, const bf16* c2 = nullptr, const float* l1 = nullptr, const float* l2 = nullptr) {
;     ...
;     for (int i = 0; i < 4; ++i) { const int row = i * 8 + (lane >> 3), ch = lane & 7; u32x4 v = *(const u32x4*)(stg + row * 64 + ch * 8);
;       const long off = ((long)(tq0 + row) * dil + r) * LD + ch * 8;
;       if (c1) { const long tok = (long)(tq0 + row); const float a0 = ws[32 + row], a1 = __builtin_nontemporal_load(l1 + tok * 8), a2 = __builtin_nontemporal_load(l2 + tok * 8); const u32x4 x1 = __builtin_nontemporal_load((const u32x4*)(c1 + off)), x2 = __builtin_nontemporal_load((const u32x4*)(c2 + off));
;         const float mxl = fmaxf(a0, fmaxf(a1, a2)); float w0 = __builtin_amdgcn_exp2f(a0 - mxl), w1 = __builtin_amdgcn_exp2f(a1 - mxl), w2 = __builtin_amdgcn_exp2f(a2 - mxl); const float inv = __builtin_amdgcn_rcpf(w0 + w1 + w2); w0 *= inv; w1 *= inv; w2 *= inv;
; #pragma unroll
;         for (int k = 0; k < 4; ++k) { const float lo = w0 * blo(v[k]) + w1 * blo(x1[k]) + w2 * blo(x2[k]), hh = w0 * bhi(v[k]) + w1 * bhi(x1[k]) + w2 * bhi(x2[k]); v[k] = cvtpk(lo, hh); } }
;       *(u32x4*)(op + off) = v; } }
	v_mov_b32_e32 v9, v164
	v_mov_b32_e32 v10, v165
	v_max3_f32 v11, v14, v9, v10
	v_sub_f32_e32 v14, v14, v11
	v_sub_f32_e32 v9, v9, v11
	v_exp_f32_e32 v17, v14
	v_exp_f32_e32 v16, v9
	v_sub_f32_e32 v9, v10, v11
	v_exp_f32_e32 v18, v9
	s_waitcnt vmcnt(7)
	v_mov_b64_e32 v[0:1], v[166:167]
	v_mov_b64_e32 v[2:3], v[168:169]
	v_and_b32_e32 v23, 0xffff0000, v0
	v_add_f32_e32 v9, v17, v16
	v_lshlrev_b32_e32 v20, 16, v0
	v_add_f32_e32 v9, v18, v9
	v_rcp_f32_e32 v14, v9
	ds_read_b128 v[8:11], v8
	s_waitcnt vmcnt(6)
	v_mov_b64_e32 v[4:5], v[170:171]
	v_mov_b64_e32 v[6:7], v[172:173]
	v_lshlrev_b32_e32 v24, 16, v4
	v_and_b32_e32 v25, 0xffff0000, v4
	v_pk_mul_f32 v[16:17], v[16:17], v[14:15] op_sel_hi:[1,0]
	v_mul_f32_e32 v18, v18, v14
	s_waitcnt lgkmcnt(0)
	v_lshlrev_b32_e32 v22, 16, v8
	v_and_b32_e32 v21, 0xffff0000, v8
	v_pk_mul_f32 v[22:23], v[16:17], v[22:23] op_sel:[1,0] op_sel_hi:[0,1]
	v_pk_fma_f32 v[20:21], v[16:17], v[20:21], v[22:23]
	v_lshlrev_b32_e32 v8, 16, v9
	v_pk_fma_f32 v[20:21], v[18:19], v[24:25], v[20:21] op_sel_hi:[0,1,1]
	v_cvt_pk_bf16_f32 v0, v20, v21
	v_and_b32_e32 v21, 0xffff0000, v9
	v_and_b32_e32 v9, 0xffff0000, v1
	v_lshlrev_b32_e32 v20, 16, v1
	v_pk_mul_f32 v[8:9], v[16:17], v[8:9] op_sel:[1,0] op_sel_hi:[0,1]
	v_lshlrev_b32_e32 v4, 16, v5
	v_and_b32_e32 v5, 0xffff0000, v5
	v_pk_fma_f32 v[8:9], v[16:17], v[20:21], v[8:9]
	v_lshlrev_b32_e32 v20, 16, v6
	v_pk_fma_f32 v[4:5], v[18:19], v[4:5], v[8:9] op_sel_hi:[0,1,1]
	v_lshlrev_b32_e32 v8, 16, v10
	v_and_b32_e32 v9, 0xffff0000, v2
	v_cvt_pk_bf16_f32 v1, v4, v5
	v_lshlrev_b32_e32 v4, 16, v2
	v_and_b32_e32 v5, 0xffff0000, v10
	v_pk_mul_f32 v[8:9], v[16:17], v[8:9] op_sel:[1,0] op_sel_hi:[0,1]
	v_and_b32_e32 v21, 0xffff0000, v6
	v_pk_fma_f32 v[4:5], v[16:17], v[4:5], v[8:9]
	v_lshlrev_b32_e32 v8, 16, v11
	v_pk_fma_f32 v[4:5], v[18:19], v[20:21], v[4:5] op_sel_hi:[0,1,1]
	v_and_b32_e32 v9, 0xffff0000, v3
	v_cvt_pk_bf16_f32 v2, v4, v5
	v_lshlrev_b32_e32 v4, 16, v3
	v_and_b32_e32 v5, 0xffff0000, v11
	v_pk_mul_f32 v[8:9], v[16:17], v[8:9] op_sel:[1,0] op_sel_hi:[0,1]
	v_pk_fma_f32 v[4:5], v[16:17], v[4:5], v[8:9]
	v_lshlrev_b32_e32 v6, 16, v7
	v_and_b32_e32 v7, 0xffff0000, v7
	v_pk_fma_f32 v[4:5], v[18:19], v[6:7], v[4:5] op_sel_hi:[0,1,1]
	v_cvt_pk_bf16_f32 v3, v4, v5
	v_lshl_add_u64 v[4:5], s[16:17], 0, v[12:13]
	v_or_b32_e32 v8, 24, v19
	global_store_dwordx4 v[4:5], v[0:3], off
	s_nop 1
	v_or_b32_e32 v0, s57, v8
	v_ashrrev_i32_e32 v1, 31, v0
	v_lshlrev_b64 v[12:13], 10, v[0:1]
	v_lshlrev_b64 v[2:3], 5, v[0:1]
	v_or_b32_e32 v12, v12, v188
	v_lshl_add_u64 v[4:5], s[40:41], 0, v[2:3]
	v_lshl_add_u64 v[2:3], s[42:43], 0, v[2:3]
	v_lshl_add_u64 v[0:1], s[22:23], 0, v[12:13]
	s_nop 0
	v_lshl_add_u64 v[4:5], s[38:39], 0, v[12:13]
	v_lshl_add_u32 v8, v8, 7, v27
	ds_read_b128 v[8:11], v8
	s_waitcnt lgkmcnt(0)
	v_and_b32_e32 v19, 0xffff0000, v9
	v_lshlrev_b32_e32 v14, 16, v9
	v_and_b32_e32 v17, 0xffff0000, v8
	v_lshlrev_b32_e32 v8, 16, v8
	s_waitcnt vmcnt(5)
	v_mov_b32_e32 v18, v174
	v_mov_b32_e32 v20, v175
	v_max3_f32 v9, v15, v18, v20
	v_sub_f32_e32 v15, v15, v9
	v_sub_f32_e32 v18, v18, v9
	v_sub_f32_e32 v9, v20, v9
	v_exp_f32_e32 v21, v15
	v_exp_f32_e32 v20, v18
	v_exp_f32_e32 v24, v9
	s_waitcnt vmcnt(4)
	v_mov_b64_e32 v[0:1], v[176:177]
	v_mov_b64_e32 v[2:3], v[178:179]
	v_lshlrev_b32_e32 v16, 16, v0
	v_and_b32_e32 v9, 0xffff0000, v0
	v_add_f32_e32 v0, v21, v20
	v_add_f32_e32 v0, v24, v0
	v_rcp_f32_e32 v0, v0
	v_and_b32_e32 v15, 0xffff0000, v1
	s_waitcnt vmcnt(3)
	v_mov_b64_e32 v[4:5], v[180:181]
	v_mov_b64_e32 v[6:7], v[182:183]
	v_lshlrev_b32_e32 v22, 16, v4
	v_and_b32_e32 v23, 0xffff0000, v4
	v_pk_mul_f32 v[20:21], v[20:21], v[0:1] op_sel_hi:[1,0]
	v_lshlrev_b32_e32 v18, 16, v1
	v_mul_f32_e32 v4, v24, v0
	v_pk_mul_f32 v[0:1], v[20:21], v[8:9] op_sel:[1,0] op_sel_hi:[0,1]
	v_pk_mul_f32 v[14:15], v[20:21], v[14:15] op_sel:[1,0] op_sel_hi:[0,1]
	v_pk_fma_f32 v[0:1], v[20:21], v[16:17], v[0:1]
	v_lshlrev_b32_e32 v8, 16, v5
	v_and_b32_e32 v9, 0xffff0000, v5
	v_pk_fma_f32 v[14:15], v[20:21], v[18:19], v[14:15]
	v_pk_fma_f32 v[0:1], v[4:5], v[22:23], v[0:1] op_sel_hi:[0,1,1]
	v_pk_fma_f32 v[8:9], v[4:5], v[8:9], v[14:15] op_sel_hi:[0,1,1]
	v_lshlrev_b32_e32 v14, 16, v10
	v_and_b32_e32 v15, 0xffff0000, v2
	v_cvt_pk_bf16_f32 v0, v0, v1
	v_cvt_pk_bf16_f32 v1, v8, v9
	v_lshlrev_b32_e32 v8, 16, v2
	v_and_b32_e32 v9, 0xffff0000, v10
	v_pk_mul_f32 v[14:15], v[20:21], v[14:15] op_sel:[1,0] op_sel_hi:[0,1]
	v_lshlrev_b32_e32 v16, 16, v6
	v_and_b32_e32 v17, 0xffff0000, v6
	v_pk_fma_f32 v[8:9], v[20:21], v[8:9], v[14:15]
	v_lshlrev_b32_e32 v10, 16, v11
	v_pk_fma_f32 v[8:9], v[4:5], v[16:17], v[8:9] op_sel_hi:[0,1,1]
	v_cvt_pk_bf16_f32 v2, v8, v9
	v_and_b32_e32 v9, 0xffff0000, v11
	v_and_b32_e32 v11, 0xffff0000, v3
	v_lshlrev_b32_e32 v8, 16, v3
	v_pk_mul_f32 v[10:11], v[20:21], v[10:11] op_sel:[1,0] op_sel_hi:[0,1]
	v_pk_fma_f32 v[8:9], v[20:21], v[8:9], v[10:11]
	v_lshlrev_b32_e32 v6, 16, v7
	v_and_b32_e32 v7, 0xffff0000, v7
	v_pk_fma_f32 v[4:5], v[4:5], v[6:7], v[8:9] op_sel_hi:[0,1,1]
	v_cvt_pk_bf16_f32 v3, v4, v5
	v_lshl_add_u64 v[4:5], s[16:17], 0, v[12:13]
	global_store_dwordx4 v[4:5], v[0:3], off
	s_barrier
	s_cbranch_scc1 .LBB0_405
